# v118 + hot loop heads (in-proj, V-transpose, diff-attn, stick-breaking, out-proj, gate GEMM) pinned to 64-byte phase with s_nop padding
# speedup vs baseline: 1.0055x; 1.0007x over previous
.LBB0_264:
	s_ashr_i32 s55, s54, 31
	s_lshl_b64 s[56:57], s[54:55], 20
	s_add_u32 s56, s10, s56
	s_addc_u32 s57, s11, s57
	s_and_b64 s[58:59], s[4:5], exec
	s_cselect_b32 s55, s57, s63
	s_cselect_b32 s61, s56, s62
	s_ashr_i32 s51, s50, 31
	s_lshl_b64 s[58:59], s[50:51], 20
	s_add_u32 s58, s46, s58
	s_addc_u32 s59, s47, s59
	s_and_b64 s[66:67], s[4:5], exec
	s_cselect_b32 s51, s59, s65
	s_cselect_b32 s68, s58, s64
	s_add_u32 s62, s62, 0x80080
	s_addc_u32 s63, s63, 0
	s_add_u32 s69, s64, 0x100
	v_mov_b32_e32 v0, 0
	s_addc_u32 s94, s65, 0
	s_mov_b32 s95, -2
	v_mov_b32_e32 v1, v0
	v_mov_b32_e32 v2, v0
	v_mov_b32_e32 v3, v0
	v_mov_b32_e32 v4, v0
	v_mov_b32_e32 v5, v0
	v_mov_b32_e32 v6, v0
	v_mov_b32_e32 v7, v0
	s_waitcnt vmcnt(0)
	v_mov_b32_e32 v16, v0
	v_mov_b32_e32 v17, v0
	v_mov_b32_e32 v18, v0
	v_mov_b32_e32 v19, v0
	v_mov_b32_e32 v20, v0
	v_mov_b32_e32 v21, v0
	v_mov_b32_e32 v22, v0
	v_mov_b32_e32 v23, v0
	v_mov_b32_e32 v32, v0
	v_mov_b32_e32 v33, v0
	v_mov_b32_e32 v34, v0
	v_mov_b32_e32 v35, v0
	v_mov_b32_e32 v36, v0
	v_mov_b32_e32 v37, v0
	v_mov_b32_e32 v38, v0
	v_mov_b32_e32 v39, v0
	v_mov_b32_e32 v48, v0
	v_mov_b32_e32 v49, v0
	v_mov_b32_e32 v50, v0
	v_mov_b32_e32 v51, v0
	v_mov_b32_e32 v52, v0
	v_mov_b32_e32 v53, v0
	v_mov_b32_e32 v54, v0
	v_mov_b32_e32 v55, v0
	v_mov_b32_e32 v8, v0
	v_mov_b32_e32 v9, v0
	v_mov_b32_e32 v10, v0
	v_mov_b32_e32 v11, v0
	v_mov_b32_e32 v12, v0
	v_mov_b32_e32 v13, v0
	v_mov_b32_e32 v14, v0
	v_mov_b32_e32 v15, v0
	v_mov_b32_e32 v24, v0
	v_mov_b32_e32 v25, v0
	v_mov_b32_e32 v26, v0
	v_mov_b32_e32 v27, v0
	v_mov_b32_e32 v28, v0
	v_mov_b32_e32 v29, v0
	v_mov_b32_e32 v30, v0
	v_mov_b32_e32 v31, v0
	v_mov_b32_e32 v40, v0
	v_mov_b32_e32 v41, v0
	v_mov_b32_e32 v42, v0
	v_mov_b32_e32 v43, v0
	v_mov_b32_e32 v44, v0
	v_mov_b32_e32 v45, v0
	v_mov_b32_e32 v46, v0
	v_mov_b32_e32 v47, v0
	v_mov_b32_e32 v56, v0
	v_mov_b32_e32 v57, v0
	v_mov_b32_e32 v58, v0
	v_mov_b32_e32 v59, v0
	v_mov_b32_e32 v60, v0
	v_mov_b32_e32 v61, v0
	v_mov_b32_e32 v62, v0
	v_mov_b32_e32 v63, v0
	v_mov_b32_e32 v64, v0
	v_mov_b32_e32 v65, v0
	v_mov_b32_e32 v66, v0
	v_mov_b32_e32 v67, v0
	v_mov_b32_e32 v68, v0
	v_mov_b32_e32 v69, v0
	v_mov_b32_e32 v70, v0
	v_mov_b32_e32 v71, v0
	v_mov_b32_e32 v80, v0
	v_mov_b32_e32 v81, v0
	v_mov_b32_e32 v82, v0
	v_mov_b32_e32 v83, v0
	v_mov_b32_e32 v84, v0
	v_mov_b32_e32 v85, v0
	v_mov_b32_e32 v86, v0
	v_mov_b32_e32 v87, v0
	v_mov_b32_e32 v96, v0
	v_mov_b32_e32 v97, v0
	v_mov_b32_e32 v98, v0
	v_mov_b32_e32 v99, v0
	v_mov_b32_e32 v100, v0
	v_mov_b32_e32 v101, v0
	v_mov_b32_e32 v102, v0
	v_mov_b32_e32 v103, v0
	v_mov_b32_e32 v112, v0
	v_mov_b32_e32 v113, v0
	v_mov_b32_e32 v114, v0
	v_mov_b32_e32 v115, v0
	v_mov_b32_e32 v116, v0
	v_mov_b32_e32 v117, v0
	v_mov_b32_e32 v118, v0
	v_mov_b32_e32 v119, v0
	v_mov_b32_e32 v72, v0
	v_mov_b32_e32 v73, v0
	v_mov_b32_e32 v74, v0
	v_mov_b32_e32 v75, v0
	v_mov_b32_e32 v76, v0
	v_mov_b32_e32 v77, v0
	v_mov_b32_e32 v78, v0
	v_mov_b32_e32 v79, v0
	v_mov_b32_e32 v88, v0
	v_mov_b32_e32 v89, v0
	v_mov_b32_e32 v90, v0
	v_mov_b32_e32 v91, v0
	v_mov_b32_e32 v92, v0
	v_mov_b32_e32 v93, v0
	v_mov_b32_e32 v94, v0
	v_mov_b32_e32 v95, v0
	v_mov_b32_e32 v104, v0
	v_mov_b32_e32 v105, v0
	v_mov_b32_e32 v106, v0
	v_mov_b32_e32 v107, v0
	v_mov_b32_e32 v108, v0
	v_mov_b32_e32 v109, v0
	v_mov_b32_e32 v110, v0
	v_mov_b32_e32 v111, v0
	v_mov_b32_e32 v120, v0
	v_mov_b32_e32 v121, v0
	v_mov_b32_e32 v122, v0
	v_mov_b32_e32 v123, v0
	v_mov_b32_e32 v124, v0
	v_mov_b32_e32 v125, v0
	v_mov_b32_e32 v126, v0
	v_mov_b32_e32 v127, v0
	s_nop 0
	s_nop 0
	s_nop 0
	s_nop 0
	s_nop 0
	s_nop 0
	s_nop 0
	s_nop 0
	s_nop 0
	s_nop 0
	s_nop 0
	s_nop 0
	s_nop 0
	s_nop 0
	s_nop 0

.LBB0_488:
	s_ashr_i32 s45, s44, 31
	s_lshl_b64 s[46:47], s[44:45], 20
	s_add_u32 s46, s61, s46
	s_addc_u32 s47, s62, s47
	s_and_b64 s[48:49], s[4:5], exec
	s_cselect_b32 s45, s47, s55
	s_cselect_b32 s51, s46, s54
	s_ashr_i32 s43, s42, 31
	s_lshl_b64 s[48:49], s[42:43], 20
	s_add_u32 s48, s10, s48
	s_addc_u32 s49, s11, s49
	s_and_b64 s[58:59], s[4:5], exec
	s_cselect_b32 s43, s49, s57
	s_cselect_b32 s83, s48, s56
	s_add_u32 s54, s54, 0x80080
	s_addc_u32 s55, s55, 0
	s_add_u32 s84, s56, 0x100
	v_mov_b32_e32 v0, 0
	s_addc_u32 s85, s57, 0
	s_mov_b32 s86, -2
	v_mov_b32_e32 v1, v0
	v_mov_b32_e32 v2, v0
	v_mov_b32_e32 v3, v0
	v_mov_b32_e32 v4, v0
	v_mov_b32_e32 v5, v0
	v_mov_b32_e32 v6, v0
	v_mov_b32_e32 v7, v0
	v_mov_b32_e32 v8, v0
	v_mov_b32_e32 v9, v0
	v_mov_b32_e32 v10, v0
	v_mov_b32_e32 v11, v0
	v_mov_b32_e32 v16, v0
	v_mov_b32_e32 v17, v0
	v_mov_b32_e32 v18, v0
	v_mov_b32_e32 v19, v0
	v_mov_b32_e32 v24, v0
	v_mov_b32_e32 v25, v0
	v_mov_b32_e32 v26, v0
	v_mov_b32_e32 v27, v0
	v_mov_b32_e32 v32, v0
	v_mov_b32_e32 v33, v0
	v_mov_b32_e32 v34, v0
	v_mov_b32_e32 v35, v0
	v_mov_b32_e32 v40, v0
	v_mov_b32_e32 v41, v0
	v_mov_b32_e32 v42, v0
	v_mov_b32_e32 v43, v0
	v_mov_b32_e32 v48, v0
	v_mov_b32_e32 v49, v0
	v_mov_b32_e32 v50, v0
	v_mov_b32_e32 v51, v0
	v_mov_b32_e32 v12, v0
	v_mov_b32_e32 v13, v0
	v_mov_b32_e32 v14, v0
	v_mov_b32_e32 v15, v0
	v_mov_b32_e32 v20, v0
	v_mov_b32_e32 v21, v0
	v_mov_b32_e32 v22, v0
	v_mov_b32_e32 v23, v0
	v_mov_b32_e32 v28, v0
	v_mov_b32_e32 v29, v0
	v_mov_b32_e32 v30, v0
	v_mov_b32_e32 v31, v0
	v_mov_b32_e32 v36, v0
	v_mov_b32_e32 v37, v0
	v_mov_b32_e32 v38, v0
	v_mov_b32_e32 v39, v0
	v_mov_b32_e32 v44, v0
	v_mov_b32_e32 v45, v0
	v_mov_b32_e32 v46, v0
	v_mov_b32_e32 v47, v0
	v_mov_b32_e32 v52, v0
	v_mov_b32_e32 v53, v0
	v_mov_b32_e32 v54, v0
	v_mov_b32_e32 v55, v0
	v_mov_b32_e32 v56, v0
	v_mov_b32_e32 v57, v0
	v_mov_b32_e32 v58, v0
	v_mov_b32_e32 v59, v0
	v_mov_b32_e32 v60, v0
	v_mov_b32_e32 v61, v0
	v_mov_b32_e32 v62, v0
	v_mov_b32_e32 v63, v0
	v_mov_b32_e32 v64, v0
	v_mov_b32_e32 v65, v0
	v_mov_b32_e32 v66, v0
	v_mov_b32_e32 v67, v0
	v_mov_b32_e32 v68, v0
	v_mov_b32_e32 v69, v0
	v_mov_b32_e32 v70, v0
	v_mov_b32_e32 v71, v0
	v_mov_b32_e32 v72, v0
	v_mov_b32_e32 v73, v0
	v_mov_b32_e32 v74, v0
	v_mov_b32_e32 v75, v0
	v_mov_b32_e32 v80, v0
	v_mov_b32_e32 v81, v0
	v_mov_b32_e32 v82, v0
	v_mov_b32_e32 v83, v0
	v_mov_b32_e32 v88, v0
	v_mov_b32_e32 v89, v0
	v_mov_b32_e32 v90, v0
	v_mov_b32_e32 v91, v0
	v_mov_b32_e32 v96, v0
	v_mov_b32_e32 v97, v0
	v_mov_b32_e32 v98, v0
	v_mov_b32_e32 v99, v0
	v_mov_b32_e32 v104, v0
	v_mov_b32_e32 v105, v0
	v_mov_b32_e32 v106, v0
	v_mov_b32_e32 v107, v0
	v_mov_b32_e32 v112, v0
	v_mov_b32_e32 v113, v0
	v_mov_b32_e32 v114, v0
	v_mov_b32_e32 v115, v0
	v_mov_b32_e32 v76, v0
	v_mov_b32_e32 v77, v0
	v_mov_b32_e32 v78, v0
	v_mov_b32_e32 v79, v0
	v_mov_b32_e32 v84, v0
	v_mov_b32_e32 v85, v0
	v_mov_b32_e32 v86, v0
	v_mov_b32_e32 v87, v0
	v_mov_b32_e32 v92, v0
	v_mov_b32_e32 v93, v0
	v_mov_b32_e32 v94, v0
	v_mov_b32_e32 v95, v0
	v_mov_b32_e32 v100, v0
	v_mov_b32_e32 v101, v0
	v_mov_b32_e32 v102, v0
	v_mov_b32_e32 v103, v0
	v_mov_b32_e32 v108, v0
	v_mov_b32_e32 v109, v0
	v_mov_b32_e32 v110, v0
	v_mov_b32_e32 v111, v0
	v_mov_b32_e32 v116, v0
	v_mov_b32_e32 v117, v0
	v_mov_b32_e32 v118, v0
	v_mov_b32_e32 v119, v0
	v_mov_b32_e32 v120, v0
	v_mov_b32_e32 v121, v0
	v_mov_b32_e32 v122, v0
	v_mov_b32_e32 v123, v0
	v_mov_b32_e32 v124, v0
	v_mov_b32_e32 v125, v0
	v_mov_b32_e32 v126, v0
	v_mov_b32_e32 v127, v0
	s_nop 0
	s_nop 0
	s_nop 0
	s_nop 0
	s_nop 0
	s_nop 0
	s_nop 0

.LBB0_553:
	s_or_b32 s4, s63, s60
	v_mov_b32_e32 v233, v225
	s_bitcmp0_b32 s63, 0
	s_cselect_b32 s70, s59, s61
	v_readfirstlane_b32 s68, v233
	s_bfe_u32 s65, s68, 0x20006
	s_lshl_b32 s71, s70, 7
	s_lshl_b32 s67, s65, 5
	v_and_b32_e32 v231, 31, v233
	s_or_b32 s69, s67, s71
	s_add_i32 s40, s4, s62
	v_or_b32_e32 v212, s69, v231
	s_ashr_i32 s41, s40, 31
	s_ashr_i32 s66, s68, 8
	s_lshl_b64 s[42:43], s[40:41], 19
	v_lshl_add_u64 v[0:1], s[38:39], 0, v[212:213]
	s_add_u32 s72, s14, s42
	v_mad_u64_u32 v[2:3], s[40:41], v0, s44, v[214:215]
	s_addc_u32 s73, s15, s43
	v_mad_i32_i24 v3, v1, s44, v3
	s_lshl_b32 s64, s4, 7
	s_lshl_b32 s4, s4, 8
	s_lshl_b32 s40, s66, 6
	v_bfe_u32 v4, v233, 5, 1
	v_lshl_add_u64 v[0:1], v[2:3], 0, s[4:5]
	s_ashr_i32 s41, s40, 31
	v_lshl_add_u64 v[0:1], s[40:41], 1, v[0:1]
	v_lshlrev_b32_e32 v216, 4, v4
	v_mov_b32_e32 v217, v213
	v_lshl_add_u64 v[0:1], v[0:1], 0, v[216:217]
	v_lshl_add_u64 v[2:3], v[0:1], 0, s[6:7]
	v_add_co_u32_e32 v0, vcc, s45, v0
	s_add_u32 s42, s81, s42
	s_nop 0
	v_addc_co_u32_e32 v1, vcc, 0, v1, vcc
	global_load_dwordx4 v[128:131], v[2:3], off offset:32
	global_load_dwordx4 v[132:135], v[2:3], off offset:64
	global_load_dwordx4 v[136:139], v[0:1], off offset:2048
	global_load_dwordx4 v[140:143], v[2:3], off offset:96
	v_lshlrev_b32_e32 v0, 3, v233
	s_addc_u32 s43, s82, s43
	v_ashrrev_i32_e32 v1, 31, v0
	s_lshl_b32 s41, s70, 1
	v_lshlrev_b64 v[0:1], 1, v[0:1]
	v_mov_b32_e32 v246, v0
	v_add_u32_e32 v245, 0x2000, v0
	s_or_b32 s70, s41, 1
	s_mov_b64 s[88:89], s[72:73]
	v_lshl_add_u64 v[218:219], s[72:73], 0, v[0:1]
	s_lshl_b32 s4, s70, 14
	s_mov_b64 s[90:91], s[42:43]
	v_lshl_add_u64 v[220:221], s[42:43], 0, v[0:1]
	v_lshl_add_u64 v[0:1], v[218:219], 0, s[4:5]
	s_barrier
	v_lshl_add_u64 v[2:3], v[220:221], 0, s[4:5]
	global_load_dwordx4 v[144:147], v[0:1], off
	global_load_dwordx4 v[148:151], v[2:3], off
	v_add_co_u32_e32 v0, vcc, s47, v0
	v_lshlrev_b32_e32 v217, 3, v4
	s_nop 0
	v_addc_co_u32_e32 v1, vcc, 0, v1, vcc
	v_add_co_u32_e32 v2, vcc, s47, v2
	v_mul_u32_u24_e32 v230, 0x110, v231
	s_nop 0
	v_addc_co_u32_e32 v3, vcc, 0, v3, vcc
	global_load_dwordx4 v[152:155], v[0:1], off
	global_load_dwordx4 v[156:159], v[2:3], off
	v_lshrrev_b32_e32 v0, 4, v233
	v_lshlrev_b32_e32 v2, 4, v233
	v_mov_b32_e32 v1, 0x14e60
	v_lshrrev_b32_e32 v3, 3, v233
	v_mul_lo_u32 v5, v0, s46
	v_and_b32_e32 v0, 0x70, v2
	v_and_b32_e32 v6, 0xf0, v2
	v_mad_u64_u32 v[222:223], s[42:43], v3, s48, v[0:1]
	v_add3_u32 v234, 0, v5, v6
	v_add_u32_e32 v0, 0, v222
	v_or_b32_e32 v2, s40, v217
	v_lshlrev_b32_e32 v2, 1, v2
	v_mov_b32_e32 v48, v213
	v_mov_b32_e32 v49, v213
	v_mov_b32_e32 v62, v213
	v_mov_b32_e32 v63, v213
	v_lshlrev_b32_e32 v232, 2, v4
	v_add3_u32 v235, 0, v230, v2
	v_mad_u32_u24 v236, v231, s48, v1
	v_mov_b32_e32 v50, v213
	v_mov_b32_e32 v51, v213
	v_mov_b32_e32 v52, v213
	v_mov_b32_e32 v53, v213
	v_mov_b32_e32 v54, v213
	v_mov_b32_e32 v55, v213
	v_mov_b32_e32 v56, v213
	v_mov_b32_e32 v57, v213
	v_mov_b32_e32 v58, v213
	v_mov_b32_e32 v59, v213
	v_mov_b32_e32 v60, v213
	v_mov_b32_e32 v61, v213
	v_mov_b64_e32 v[32:33], v[48:49]
	v_mov_b64_e32 v[16:17], v[48:49]
	s_waitcnt vmcnt(8)
	v_mov_b64_e32 v[78:79], v[62:63]
	s_mov_b32 s72, 1
	s_waitcnt vmcnt(3)
	ds_write_b128 v234, v[144:147]
	s_waitcnt vmcnt(2)
	ds_write_b128 v0, v[148:151] offset:34816
	s_waitcnt vmcnt(1)
	ds_write_b128 v234, v[152:155] offset:8704
	s_waitcnt vmcnt(0)
	ds_write_b128 v0, v[156:159] offset:44032
	v_mov_b32_e32 v0, 0x14e40
	v_mad_u32_u24 v237, v231, s48, v0
	v_mov_b32_e32 v0, 0x14e20
	v_mad_u32_u24 v238, v231, s48, v0
	v_mov_b32_e32 v0, 0x14e00
	v_mad_u32_u24 v239, v231, s48, v0
	v_mov_b32_e32 v0, 0x13c00
	v_mad_u32_u24 v240, v231, s48, v0
	v_mov_b32_e32 v0, 0x12a60
	v_mad_u32_u24 v241, v231, s48, v0
	v_mov_b32_e32 v0, 0x12a40
	v_mad_u32_u24 v242, v231, s48, v0
	v_mov_b32_e32 v0, 0x12a20
	v_mad_u32_u24 v243, v231, s48, v0
	v_mov_b32_e32 v0, 0x12a00
	v_mad_u32_u24 v244, v231, s48, v0
	v_mov_b32_e32 v0, 0x11800
	v_mad_u32_u24 v248, v231, s48, v0
	v_add_u32_e32 v248, v248, v216
	v_mov_b64_e32 v[0:1], v[48:49]
	s_mov_b32 s73, 0
	s_mov_b32 s74, 2
	s_or_b32 s75, s69, 31
	s_mov_b64 s[42:43], 0
	v_mov_b32_e32 v224, 1.0
	v_mov_b32_e32 v249, 0xf149f2ca
	v_mov_b32_e32 v223, 0
	s_mov_b32 s4, s41
	v_mov_b64_e32 v[34:35], v[50:51]
	v_mov_b64_e32 v[36:37], v[52:53]
	v_mov_b64_e32 v[38:39], v[54:55]
	v_mov_b64_e32 v[40:41], v[56:57]
	v_mov_b64_e32 v[42:43], v[58:59]
	v_mov_b64_e32 v[44:45], v[60:61]
	v_mov_b64_e32 v[46:47], v[62:63]
	v_mov_b64_e32 v[18:19], v[50:51]
	v_mov_b64_e32 v[20:21], v[52:53]
	v_mov_b64_e32 v[22:23], v[54:55]
	v_mov_b64_e32 v[24:25], v[56:57]
	v_mov_b64_e32 v[26:27], v[58:59]
	v_mov_b64_e32 v[28:29], v[60:61]
	v_mov_b64_e32 v[30:31], v[62:63]
	v_mov_b64_e32 v[2:3], v[50:51]
	v_mov_b64_e32 v[4:5], v[52:53]
	v_mov_b64_e32 v[6:7], v[54:55]
	v_mov_b64_e32 v[8:9], v[56:57]
	v_mov_b64_e32 v[10:11], v[58:59]
	v_mov_b64_e32 v[12:13], v[60:61]
	v_mov_b64_e32 v[14:15], v[62:63]
	v_mov_b64_e32 v[76:77], v[60:61]
	v_mov_b64_e32 v[74:75], v[58:59]
	v_mov_b64_e32 v[72:73], v[56:57]
	v_mov_b64_e32 v[70:71], v[54:55]
	v_mov_b64_e32 v[68:69], v[52:53]
	v_mov_b64_e32 v[66:67], v[50:51]
	v_mov_b64_e32 v[64:65], v[48:49]
	s_waitcnt lgkmcnt(0)
	s_barrier
	s_branch .LBB0_555
	s_nop 0

.LBB0_585:
	s_and_b32 s4, s63, 7
	s_lshl_b32 s5, s4, 2
	v_mov_b32_e32 v6, v225
	s_or_b32 s71, s5, 2
	s_and_b32 s42, s3, 7
	v_readfirstlane_b32 s5, v6
	s_ashr_i32 s64, s5, 6
	s_lshl_b32 s65, s4, 8
	s_ashr_i32 s4, s3, 6
	s_lshl_b32 s5, s42, 8
	s_lshl_b32 s66, s64, 5
	s_add_i32 s66, s66, s5
	s_ashr_i32 s5, s4, 31
	s_bfe_u32 s8, s3, 0x30003
	v_and_b32_e32 v7, 31, v6
	s_lshl_b64 s[38:39], s[4:5], 11
	s_lshl_b32 s4, s4, 3
	s_waitcnt vmcnt(2)
	v_or_b32_e32 v150, s66, v7
	s_or_b32 s4, s4, s8
	s_ashr_i32 s5, s4, 31
	v_ashrrev_i32_e32 v151, 31, v150
	s_lshl_b64 s[4:5], s[4:5], 19
	v_lshl_add_u64 v[2:3], s[38:39], 0, v[150:151]
	s_add_u32 s6, s14, s4
	v_mad_u64_u32 v[4:5], s[40:41], v2, s44, v[146:147]
	v_bfe_u32 v8, v6, 5, 1
	s_addc_u32 s7, s15, s5
	v_mad_i32_i24 v5, v3, s44, v5
	s_lshl_b32 s67, s8, 7
	s_lshl_b32 s8, s8, 8
	v_lshl_add_u64 v[2:3], v[4:5], 0, s[8:9]
	v_lshlrev_b32_e32 v0, 4, v8
	v_lshl_add_u64 v[2:3], v[2:3], 0, v[0:1]
	global_load_dwordx4 v[98:101], v[2:3], off
	global_load_dwordx4 v[102:105], v[2:3], off offset:32
	global_load_dwordx4 v[106:109], v[2:3], off offset:64
	global_load_dwordx4 v[110:113], v[2:3], off offset:96
	global_load_dwordx4 v[114:117], v[2:3], off offset:128
	global_load_dwordx4 v[118:121], v[2:3], off offset:160
	global_load_dwordx4 v[122:125], v[2:3], off offset:192
	global_load_dwordx4 v[126:129], v[2:3], off offset:224
	v_lshlrev_b32_e32 v2, 3, v6
	s_add_u32 s4, s81, s4
	v_ashrrev_i32_e32 v3, 31, v2
	s_addc_u32 s5, s82, s5
	v_lshlrev_b64 v[2:3], 1, v[2:3]
	v_mov_b32_e32 v228, v2
	v_add_u32_e32 v229, 0x2000, v2
	s_waitcnt vmcnt(9)
	s_mov_b64 s[90:91], s[4:5]
	v_lshl_add_u64 v[154:155], s[4:5], 0, v[2:3]
	s_lshl_b32 s4, s42, 16
	s_mov_b64 s[88:89], s[6:7]
	v_lshl_add_u64 v[152:153], s[6:7], 0, v[2:3]
	s_or_b32 s8, s4, 0xc000
	v_lshl_add_u64 v[2:3], v[152:153], 0, s[8:9]
	s_barrier
	v_lshl_add_u64 v[4:5], v[154:155], 0, s[8:9]
	global_load_dwordx4 v[130:133], v[2:3], off
	global_load_dwordx4 v[134:137], v[4:5], off
	v_add_co_u32_e32 v2, vcc, s46, v2
	v_and_b32_e32 v149, 63, v6
	s_nop 0
	v_addc_co_u32_e32 v3, vcc, 0, v3, vcc
	v_add_co_u32_e32 v4, vcc, s46, v4
	v_mul_u32_u24_e32 v197, 0x110, v7
	s_nop 0
	v_addc_co_u32_e32 v5, vcc, 0, v5, vcc
	global_load_dwordx4 v[138:141], v[2:3], off
	global_load_dwordx4 v[142:145], v[4:5], off
	v_lshlrev_b32_e32 v2, 4, v6
	v_lshrrev_b32_e32 v3, 3, v6
	v_lshrrev_b32_e32 v4, 4, v6
	v_and_b32_e32 v148, 0xf0, v2
	v_and_b32_e32 v2, 0x70, v2
	s_waitcnt vmcnt(12)
	v_mad_u64_u32 v[156:157], s[4:5], v4, s47, v[148:149]
	v_mad_u64_u32 v[158:159], s[4:5], v3, s48, v[2:3]
	v_lshlrev_b32_e32 v5, 7, v7
	v_add3_u32 v157, 0, v197, v0
	v_add_u32_e32 v0, 0, v156
	v_add_u32_e32 v2, 0, v158
	v_mov_b32_e32 v14, v1
	v_mov_b32_e32 v15, v1
	v_lshlrev_b32_e32 v151, 3, v8
	s_lshl_b32 s4, s64, 2
	v_lshlrev_b32_e32 v159, 2, v8
	v_sub_u32_e32 v198, v157, v5
	v_mov_b32_e32 v3, v1
	v_mov_b32_e32 v4, v1
	v_mov_b32_e32 v5, v1
	v_mov_b32_e32 v6, v1
	v_mov_b32_e32 v7, v1
	v_mov_b32_e32 v8, v1
	v_mov_b32_e32 v9, v1
	v_mov_b32_e32 v10, v1
	v_mov_b32_e32 v11, v1
	v_mov_b32_e32 v12, v1
	v_mov_b32_e32 v13, v1
	s_add_i32 s69, s4, 0
	v_cmp_eq_u32_e64 s[6:7], 0, v149
	s_or_b32 s68, s66, 30
	s_add_i32 s69, s69, 0x11800
	v_cmp_gt_u32_e64 s[4:5], 32, v149
	s_mov_b64 s[42:43], 0
	s_mov_b32 s70, s9
	s_mov_b32 s8, s71
	s_mov_b32 s71, s9
	s_waitcnt vmcnt(3)
	ds_write_b128 v0, v[130:133]
	s_waitcnt vmcnt(2)
	ds_write_b128 v2, v[134:137] offset:17408
	s_waitcnt vmcnt(1)
	ds_write_b128 v0, v[138:141] offset:8704
	s_waitcnt vmcnt(0)
	ds_write_b128 v2, v[142:145] offset:26624
	v_mov_b32_e32 v0, v1
	v_mov_b32_e32 v2, v1
	v_mov_b64_e32 v[64:65], v[14:15]
	v_mov_b64_e32 v[48:49], v[14:15]
	v_mov_b64_e32 v[32:33], v[14:15]
	v_mov_b64_e32 v[62:63], v[12:13]
	v_mov_b64_e32 v[60:61], v[10:11]
	v_mov_b64_e32 v[58:59], v[8:9]
	v_mov_b64_e32 v[56:57], v[6:7]
	v_mov_b64_e32 v[54:55], v[4:5]
	v_mov_b64_e32 v[52:53], v[2:3]
	v_mov_b64_e32 v[50:51], v[0:1]
	v_mov_b64_e32 v[46:47], v[12:13]
	v_mov_b64_e32 v[44:45], v[10:11]
	v_mov_b64_e32 v[42:43], v[8:9]
	v_mov_b64_e32 v[40:41], v[6:7]
	v_mov_b64_e32 v[38:39], v[4:5]
	v_mov_b64_e32 v[36:37], v[2:3]
	v_mov_b64_e32 v[34:35], v[0:1]
	v_mov_b64_e32 v[30:31], v[12:13]
	v_mov_b64_e32 v[28:29], v[10:11]
	v_mov_b64_e32 v[26:27], v[8:9]
	v_mov_b64_e32 v[24:25], v[6:7]
	v_mov_b64_e32 v[22:23], v[4:5]
	v_mov_b64_e32 v[20:21], v[2:3]
	v_mov_b64_e32 v[18:19], v[0:1]
	v_mov_b64_e32 v[16:17], v[14:15]
	v_mov_b64_e32 v[14:15], v[12:13]
	v_mov_b64_e32 v[12:13], v[10:11]
	v_mov_b64_e32 v[10:11], v[8:9]
	v_mov_b64_e32 v[8:9], v[6:7]
	v_mov_b64_e32 v[6:7], v[4:5]
	v_mov_b64_e32 v[4:5], v[2:3]
	v_mov_b64_e32 v[2:3], v[0:1]
	v_mov_b32_e32 v0, 0
	s_waitcnt lgkmcnt(0)
	s_barrier
	s_branch .LBB0_587
	s_nop 0
	s_nop 0
	s_nop 0
	s_nop 0
	s_nop 0
	s_nop 0
	s_nop 0
	s_nop 0
	s_nop 0
	s_nop 0
	s_nop 0
	s_nop 0
	s_nop 0
	s_nop 0
	s_nop 0

.LBB0_671:
	s_ashr_i32 s51, s50, 31
	s_lshl_b64 s[52:53], s[50:51], 20
	s_add_u32 s52, s10, s52
	s_addc_u32 s53, s11, s53
	s_and_b64 s[54:55], s[6:7], exec
	s_cselect_b32 s51, s53, s61
	s_cselect_b32 s57, s52, s60
	s_ashr_i32 s49, s48, 31
	s_lshl_b64 s[54:55], s[48:49], 20
	s_add_u32 s54, s34, s54
	s_addc_u32 s55, s35, s55
	s_and_b64 s[64:65], s[6:7], exec
	s_cselect_b32 s49, s55, s63
	s_cselect_b32 s77, s54, s62
	s_add_u32 s60, s60, 0x80080
	s_addc_u32 s61, s61, 0
	s_add_u32 s81, s62, 0x100
	v_mov_b32_e32 v0, 0
	s_addc_u32 s82, s63, 0
	s_mov_b32 s83, -2
	s_waitcnt lgkmcnt(0)
	v_mov_b32_e32 v1, v0
	v_mov_b32_e32 v2, v0
	v_mov_b32_e32 v3, v0
	v_mov_b32_e32 v4, v0
	v_mov_b32_e32 v5, v0
	v_mov_b32_e32 v6, v0
	v_mov_b32_e32 v7, v0
	v_mov_b32_e32 v16, v0
	v_mov_b32_e32 v17, v0
	v_mov_b32_e32 v18, v0
	v_mov_b32_e32 v19, v0
	v_mov_b32_e32 v20, v0
	v_mov_b32_e32 v21, v0
	v_mov_b32_e32 v22, v0
	v_mov_b32_e32 v23, v0
	v_mov_b32_e32 v32, v0
	v_mov_b32_e32 v33, v0
	v_mov_b32_e32 v34, v0
	v_mov_b32_e32 v35, v0
	v_mov_b32_e32 v36, v0
	v_mov_b32_e32 v37, v0
	v_mov_b32_e32 v38, v0
	v_mov_b32_e32 v39, v0
	v_mov_b32_e32 v48, v0
	v_mov_b32_e32 v49, v0
	v_mov_b32_e32 v50, v0
	v_mov_b32_e32 v51, v0
	v_mov_b32_e32 v52, v0
	v_mov_b32_e32 v53, v0
	v_mov_b32_e32 v54, v0
	v_mov_b32_e32 v55, v0
	v_mov_b32_e32 v8, v0
	v_mov_b32_e32 v9, v0
	v_mov_b32_e32 v10, v0
	v_mov_b32_e32 v11, v0
	v_mov_b32_e32 v12, v0
	v_mov_b32_e32 v13, v0
	v_mov_b32_e32 v14, v0
	v_mov_b32_e32 v15, v0
	v_mov_b32_e32 v24, v0
	v_mov_b32_e32 v25, v0
	v_mov_b32_e32 v26, v0
	v_mov_b32_e32 v27, v0
	v_mov_b32_e32 v28, v0
	v_mov_b32_e32 v29, v0
	v_mov_b32_e32 v30, v0
	v_mov_b32_e32 v31, v0
	v_mov_b32_e32 v40, v0
	v_mov_b32_e32 v41, v0
	v_mov_b32_e32 v42, v0
	v_mov_b32_e32 v43, v0
	v_mov_b32_e32 v44, v0
	v_mov_b32_e32 v45, v0
	v_mov_b32_e32 v46, v0
	v_mov_b32_e32 v47, v0
	v_mov_b32_e32 v56, v0
	v_mov_b32_e32 v57, v0
	v_mov_b32_e32 v58, v0
	v_mov_b32_e32 v59, v0
	v_mov_b32_e32 v60, v0
	v_mov_b32_e32 v61, v0
	v_mov_b32_e32 v62, v0
	v_mov_b32_e32 v63, v0
	v_mov_b32_e32 v64, v0
	v_mov_b32_e32 v65, v0
	v_mov_b32_e32 v66, v0
	v_mov_b32_e32 v67, v0
	v_mov_b32_e32 v68, v0
	v_mov_b32_e32 v69, v0
	v_mov_b32_e32 v70, v0
	v_mov_b32_e32 v71, v0
	v_mov_b32_e32 v80, v0
	v_mov_b32_e32 v81, v0
	v_mov_b32_e32 v82, v0
	v_mov_b32_e32 v83, v0
	v_mov_b32_e32 v84, v0
	v_mov_b32_e32 v85, v0
	v_mov_b32_e32 v86, v0
	v_mov_b32_e32 v87, v0
	v_mov_b32_e32 v96, v0
	v_mov_b32_e32 v97, v0
	v_mov_b32_e32 v98, v0
	v_mov_b32_e32 v99, v0
	v_mov_b32_e32 v100, v0
	v_mov_b32_e32 v101, v0
	v_mov_b32_e32 v102, v0
	v_mov_b32_e32 v103, v0
	v_mov_b32_e32 v112, v0
	v_mov_b32_e32 v113, v0
	v_mov_b32_e32 v114, v0
	v_mov_b32_e32 v115, v0
	v_mov_b32_e32 v116, v0
	v_mov_b32_e32 v117, v0
	v_mov_b32_e32 v118, v0
	v_mov_b32_e32 v119, v0
	v_mov_b32_e32 v72, v0
	v_mov_b32_e32 v73, v0
	v_mov_b32_e32 v74, v0
	v_mov_b32_e32 v75, v0
	v_mov_b32_e32 v76, v0
	v_mov_b32_e32 v77, v0
	v_mov_b32_e32 v78, v0
	v_mov_b32_e32 v79, v0
	v_mov_b32_e32 v88, v0
	v_mov_b32_e32 v89, v0
	v_mov_b32_e32 v90, v0
	v_mov_b32_e32 v91, v0
	v_mov_b32_e32 v92, v0
	v_mov_b32_e32 v93, v0
	v_mov_b32_e32 v94, v0
	v_mov_b32_e32 v95, v0
	v_mov_b32_e32 v104, v0
	v_mov_b32_e32 v105, v0
	v_mov_b32_e32 v106, v0
	v_mov_b32_e32 v107, v0
	v_mov_b32_e32 v108, v0
	v_mov_b32_e32 v109, v0
	v_mov_b32_e32 v110, v0
	v_mov_b32_e32 v111, v0
	v_mov_b32_e32 v120, v0
	v_mov_b32_e32 v121, v0
	v_mov_b32_e32 v122, v0
	v_mov_b32_e32 v123, v0
	v_mov_b32_e32 v124, v0
	v_mov_b32_e32 v125, v0
	v_mov_b32_e32 v126, v0
	v_mov_b32_e32 v127, v0
	s_nop 0
	s_nop 0
	s_nop 0
	s_nop 0
	s_nop 0
	s_nop 0
	s_nop 0
	s_nop 0
	s_nop 0
	s_nop 0
	s_nop 0
	s_nop 0
	s_nop 0
	s_nop 0

.LBB0_787:
	s_ashr_i32 s39, s38, 31
	s_lshl_b64 s[40:41], s[38:39], 20
	s_add_u32 s40, s12, s40
	s_addc_u32 s41, s13, s41
	s_and_b64 s[42:43], s[4:5], exec
	s_cselect_b32 s39, s41, s49
	s_cselect_b32 s45, s40, s48
	s_ashr_i32 s37, s36, 31
	s_lshl_b64 s[42:43], s[36:37], 20
	s_add_u32 s42, s28, s42
	s_addc_u32 s43, s29, s43
	s_and_b64 s[52:53], s[4:5], exec
	s_cselect_b32 s37, s43, s51
	s_cselect_b32 s66, s42, s50
	s_add_u32 s48, s48, 0x80080
	s_addc_u32 s49, s49, 0
	s_add_u32 s67, s50, 0x100
	v_mov_b32_e32 v0, 0
	s_addc_u32 s68, s51, 0
	s_mov_b32 s69, -2
	s_waitcnt lgkmcnt(0)
	v_mov_b32_e32 v1, v0
	v_mov_b32_e32 v2, v0
	v_mov_b32_e32 v3, v0
	v_mov_b32_e32 v4, v0
	v_mov_b32_e32 v5, v0
	v_mov_b32_e32 v6, v0
	v_mov_b32_e32 v7, v0
	v_mov_b32_e32 v16, v0
	v_mov_b32_e32 v17, v0
	v_mov_b32_e32 v18, v0
	v_mov_b32_e32 v19, v0
	v_mov_b32_e32 v20, v0
	v_mov_b32_e32 v21, v0
	v_mov_b32_e32 v22, v0
	v_mov_b32_e32 v23, v0
	v_mov_b32_e32 v32, v0
	v_mov_b32_e32 v33, v0
	v_mov_b32_e32 v34, v0
	v_mov_b32_e32 v35, v0
	v_mov_b32_e32 v36, v0
	v_mov_b32_e32 v37, v0
	v_mov_b32_e32 v38, v0
	v_mov_b32_e32 v39, v0
	v_mov_b32_e32 v48, v0
	v_mov_b32_e32 v49, v0
	v_mov_b32_e32 v50, v0
	v_mov_b32_e32 v51, v0
	v_mov_b32_e32 v52, v0
	v_mov_b32_e32 v53, v0
	v_mov_b32_e32 v54, v0
	v_mov_b32_e32 v55, v0
	v_mov_b32_e32 v8, v0
	v_mov_b32_e32 v9, v0
	v_mov_b32_e32 v10, v0
	v_mov_b32_e32 v11, v0
	v_mov_b32_e32 v12, v0
	v_mov_b32_e32 v13, v0
	v_mov_b32_e32 v14, v0
	v_mov_b32_e32 v15, v0
	v_mov_b32_e32 v24, v0
	v_mov_b32_e32 v25, v0
	v_mov_b32_e32 v26, v0
	v_mov_b32_e32 v27, v0
	v_mov_b32_e32 v28, v0
	v_mov_b32_e32 v29, v0
	v_mov_b32_e32 v30, v0
	v_mov_b32_e32 v31, v0
	v_mov_b32_e32 v40, v0
	v_mov_b32_e32 v41, v0
	v_mov_b32_e32 v42, v0
	v_mov_b32_e32 v43, v0
	v_mov_b32_e32 v44, v0
	v_mov_b32_e32 v45, v0
	v_mov_b32_e32 v46, v0
	v_mov_b32_e32 v47, v0
	v_mov_b32_e32 v56, v0
	v_mov_b32_e32 v57, v0
	v_mov_b32_e32 v58, v0
	v_mov_b32_e32 v59, v0
	v_mov_b32_e32 v60, v0
	v_mov_b32_e32 v61, v0
	v_mov_b32_e32 v62, v0
	v_mov_b32_e32 v63, v0
	v_mov_b32_e32 v64, v0
	v_mov_b32_e32 v65, v0
	v_mov_b32_e32 v66, v0
	v_mov_b32_e32 v67, v0
	v_mov_b32_e32 v68, v0
	v_mov_b32_e32 v69, v0
	v_mov_b32_e32 v70, v0
	v_mov_b32_e32 v71, v0
	v_mov_b32_e32 v80, v0
	v_mov_b32_e32 v81, v0
	v_mov_b32_e32 v82, v0
	v_mov_b32_e32 v83, v0
	v_mov_b32_e32 v84, v0
	v_mov_b32_e32 v85, v0
	v_mov_b32_e32 v86, v0
	v_mov_b32_e32 v87, v0
	v_mov_b32_e32 v96, v0
	v_mov_b32_e32 v97, v0
	v_mov_b32_e32 v98, v0
	v_mov_b32_e32 v99, v0
	v_mov_b32_e32 v100, v0
	v_mov_b32_e32 v101, v0
	v_mov_b32_e32 v102, v0
	v_mov_b32_e32 v103, v0
	v_mov_b32_e32 v112, v0
	v_mov_b32_e32 v113, v0
	v_mov_b32_e32 v114, v0
	v_mov_b32_e32 v115, v0
	v_mov_b32_e32 v116, v0
	v_mov_b32_e32 v117, v0
	v_mov_b32_e32 v118, v0
	v_mov_b32_e32 v119, v0
	v_mov_b32_e32 v72, v0
	v_mov_b32_e32 v73, v0
	v_mov_b32_e32 v74, v0
	v_mov_b32_e32 v75, v0
	v_mov_b32_e32 v76, v0
	v_mov_b32_e32 v77, v0
	v_mov_b32_e32 v78, v0
	v_mov_b32_e32 v79, v0
	v_mov_b32_e32 v88, v0
	v_mov_b32_e32 v89, v0
	v_mov_b32_e32 v90, v0
	v_mov_b32_e32 v91, v0
	v_mov_b32_e32 v92, v0
	v_mov_b32_e32 v93, v0
	v_mov_b32_e32 v94, v0
	v_mov_b32_e32 v95, v0
	v_mov_b32_e32 v104, v0
	v_mov_b32_e32 v105, v0
	v_mov_b32_e32 v106, v0
	v_mov_b32_e32 v107, v0
	v_mov_b32_e32 v108, v0
	v_mov_b32_e32 v109, v0
	v_mov_b32_e32 v110, v0
	v_mov_b32_e32 v111, v0
	v_mov_b32_e32 v120, v0
	v_mov_b32_e32 v121, v0
	v_mov_b32_e32 v122, v0
	v_mov_b32_e32 v123, v0
	v_mov_b32_e32 v124, v0
	v_mov_b32_e32 v125, v0
	v_mov_b32_e32 v126, v0
	v_mov_b32_e32 v127, v0
	s_nop 0
	s_nop 0
	s_nop 0
	s_nop 0
	s_nop 0
	s_nop 0
	s_nop 0
	s_nop 0
	s_nop 0
	s_nop 0
	s_nop 0
	s_nop 0
